# attention: wave-invariant LDS-DMA destination selects removed; mp0 p0 row-sum adds ride with the deferred P.V MFMAs
# baseline (speedup 1.0000x reference)
.LBB0_638:
	s_cmpk_eq_i32 s20, 0xfc0
	s_cbranch_scc1 .Lv2p_flush
	s_add_i32 s50, s44, 0
	v_add3_u32 v84, s50, v162, v146
	ds_read_b128 v[80:83], v84
	ds_read_b128 v[128:131], v84 offset:32
	ds_read_b128 v[132:135], v84 offset:4608
	ds_read_b128 v[136:139], v84 offset:4640
	ds_read_b128 v[140:143], v84 offset:64
	ds_read_b128 v[220:223], v84 offset:96
	ds_read_b128 v[224:227], v84 offset:4672
	ds_read_b128 v[228:231], v84 offset:4704
	v_mfma_f32_32x32x16_bf16 v[32:47], v[182:185], v[170:173], v[32:47]
	v_add_f32_e32 v96, v97, v96
	v_add_f32_e32 v96, v98, v96
	v_add_f32_e32 v96, v99, v96
	v_add_f32_e32 v96, v100, v96
	v_mfma_f32_32x32x16_bf16 v[16:31], v[190:193], v[170:173], v[16:31]
	v_add_f32_e32 v96, v101, v96
	v_add_f32_e32 v96, v102, v96
	v_add_f32_e32 v96, v103, v96
	v_add_f32_e32 v96, v104, v96
	v_mfma_f32_32x32x16_bf16 v[32:47], v[186:189], v[178:181], v[32:47]
	v_add_f32_e32 v96, v105, v96
	v_add_f32_e32 v96, v106, v96
	v_add_f32_e32 v96, v107, v96
	v_add_f32_e32 v96, v108, v96
	v_mfma_f32_32x32x16_bf16 v[16:31], v[194:197], v[178:181], v[16:31]
	v_add_f32_e32 v96, v109, v96
	v_add_f32_e32 v96, v110, v96
	v_add_f32_e32 v96, v111, v96
	v_add_f32_e32 v96, v157, v96
	v_add_f32_e32 v157, v96, v251
	s_branch .Lv2p_body

.LBB0_699:
	s_cmpk_eq_i32 s20, 0x7c0
	s_cbranch_scc1 .Lv2s_flush
	s_add_i32 s56, s44, 0
	v_add3_u32 v84, s56, v162, v146
	ds_read_b128 v[80:83], v84
	ds_read_b128 v[128:131], v84 offset:32
	ds_read_b128 v[132:135], v84 offset:4608
	ds_read_b128 v[136:139], v84 offset:4640
	ds_read_b128 v[140:143], v84 offset:64
	ds_read_b128 v[220:223], v84 offset:96
	ds_read_b128 v[224:227], v84 offset:4672
	ds_read_b128 v[228:231], v84 offset:4704
	v_mfma_f32_32x32x16_bf16 v[32:47], v[182:185], v[170:173], v[32:47]
	v_add_f32_e32 v96, v97, v96
	v_add_f32_e32 v96, v98, v96
	v_add_f32_e32 v96, v99, v96
	v_add_f32_e32 v96, v100, v96
	v_mfma_f32_32x32x16_bf16 v[16:31], v[190:193], v[170:173], v[16:31]
	v_add_f32_e32 v96, v101, v96
	v_add_f32_e32 v96, v102, v96
	v_add_f32_e32 v96, v103, v96
	v_add_f32_e32 v96, v104, v96
	v_mfma_f32_32x32x16_bf16 v[32:47], v[186:189], v[178:181], v[32:47]
	v_add_f32_e32 v96, v105, v96
	v_add_f32_e32 v96, v106, v96
	v_add_f32_e32 v96, v107, v96
	v_add_f32_e32 v96, v108, v96
	v_mfma_f32_32x32x16_bf16 v[16:31], v[194:197], v[178:181], v[16:31]
	v_add_f32_e32 v96, v109, v96
	v_add_f32_e32 v96, v110, v96
	v_add_f32_e32 v96, v111, v96
	v_add_f32_e32 v96, v157, v96
	v_add_f32_e32 v157, v96, v251
	s_branch .Lv2s_body
